# first-barrier census: 16 serialized counter loads issued together (no finalize batching)
# speedup vs baseline: 1.0104x; 1.0020x over previous
; DI unsigned xb_ld(unsigned* p) { return __hip_atomic_load(p, __ATOMIC_RELAXED, __HIP_MEMORY_SCOPE_AGENT); }
; DI void xcd_barrier_complete(unsigned* bar, unsigned x, unsigned& nloc, unsigned& nx) {
;     ...
;   for (;;) {
;     sum = 0u; cnt = 0u; mine = 0u;
; #pragma unroll
;     for (unsigned j = 0; j < 16; ++j) { const unsigned c = xb_ld(&bar[XB_XCNT(j)]); sum += c; cnt += (c > 0u) ? 1u : 0u; mine = (j == x) ? c : mine; }
;     if (sum == G) break;
;     __builtin_amdgcn_s_sleep(1);
;     if ((++sp & 255u) == 0u) { if (xb_ld(&bar[XB_TMO])) break; if (sp > XB_SPIN_CAP) { atomicAdd(&bar[XB_TMO], 1u); break; } }
;   }
.LBB0_1556:
	v_readlane_b32 s6, v252, 62
	v_readlane_b32 s7, v252, 63
	s_mov_b64 s[10:11], -1
	s_nop 3
	global_load_dword v0, v3, s[6:7] sc1
	v_readlane_b32 s6, v253, 0
	v_readlane_b32 s7, v253, 1
	s_nop 4
	global_load_dword v1, v3, s[6:7] sc1
	v_readlane_b32 s6, v253, 2
	v_readlane_b32 s7, v253, 3
	s_nop 1
	s_nop 2
	global_load_dword v2, v3, s[6:7] sc1
	v_readlane_b32 s6, v253, 4
	v_readlane_b32 s7, v253, 5
	s_nop 1
	s_nop 2
	global_load_dword v4, v3, s[6:7] sc1
	v_readlane_b32 s6, v253, 6
	v_readlane_b32 s7, v253, 7
	s_nop 1
	s_nop 2
	global_load_dword v5, v3, s[6:7] sc1
	v_readlane_b32 s6, v253, 8
	v_readlane_b32 s7, v253, 9
	s_nop 1
	s_nop 2
	global_load_dword v6, v3, s[6:7] sc1
	v_readlane_b32 s6, v253, 10
	v_readlane_b32 s7, v253, 11
	s_nop 1
	s_nop 2
	global_load_dword v7, v3, s[6:7] sc1
	v_readlane_b32 s6, v253, 12
	v_readlane_b32 s7, v253, 13
	s_nop 1
	s_nop 2
	global_load_dword v8, v3, s[6:7] sc1
	v_readlane_b32 s6, v253, 14
	v_readlane_b32 s7, v253, 15
	s_nop 1
	s_nop 2
	global_load_dword v9, v3, s[6:7] sc1
	v_readlane_b32 s6, v253, 16
	v_readlane_b32 s7, v253, 17
	s_nop 1
	s_nop 2
	global_load_dword v10, v3, s[6:7] sc1
	v_readlane_b32 s6, v253, 18
	v_readlane_b32 s7, v253, 19
	s_nop 1
	s_nop 2
	global_load_dword v11, v3, s[6:7] sc1
	v_readlane_b32 s6, v253, 20
	v_readlane_b32 s7, v253, 21
	s_nop 1
	s_nop 2
	global_load_dword v12, v3, s[6:7] sc1
	v_readlane_b32 s6, v253, 22
	v_readlane_b32 s7, v253, 23
	s_nop 1
	s_nop 2
	global_load_dword v13, v3, s[6:7] sc1
	v_readlane_b32 s6, v253, 24
	v_readlane_b32 s7, v253, 25
	s_nop 1
	s_nop 2
	global_load_dword v14, v3, s[6:7] sc1
	v_readlane_b32 s6, v253, 26
	v_readlane_b32 s7, v253, 27
	s_nop 1
	s_nop 2
	global_load_dword v15, v3, s[6:7] sc1
	v_readlane_b32 s6, v253, 28
	v_readlane_b32 s7, v253, 29
	s_nop 1
	s_nop 2
	global_load_dword v16, v3, s[6:7] sc1
	s_mov_b64 s[6:7], -1
	s_waitcnt vmcnt(0)
	v_add_u32_e32 v17, v1, v0
	v_add_u32_e32 v17, v17, v2
	v_add_u32_e32 v17, v17, v4
	v_add_u32_e32 v17, v17, v5
	v_add_u32_e32 v17, v17, v6
	v_add_u32_e32 v17, v17, v7
	v_add_u32_e32 v17, v17, v8
	v_add_u32_e32 v17, v17, v9
	v_add_u32_e32 v17, v17, v10
	v_add_u32_e32 v17, v17, v11
	v_add_u32_e32 v17, v17, v12
	v_add_u32_e32 v17, v17, v13
	v_add_u32_e32 v17, v17, v14
	v_add_u32_e32 v17, v17, v15
	v_add_u32_e32 v17, v17, v16
	v_cmp_eq_u32_e32 vcc, s5, v17
	s_cbranch_vccnz .LBB0_1555
	s_and_b32 s6, s14, 0xff
	s_cmp_eq_u32 s6, 0
	s_mov_b64 s[6:7], -1
	s_mov_b64 s[12:13], -1
	s_sleep 1
	s_cbranch_scc0 .LBB0_1560
	v_readlane_b32 s6, v252, 60
	v_readlane_b32 s7, v252, 61
	s_nop 4
	global_load_dword v17, v3, s[6:7] sc1
	s_waitcnt vmcnt(0)
	v_cmp_eq_u32_e32 vcc, 0, v17
	s_cbranch_vccnz .LBB0_1562
	s_mov_b64 s[12:13], 0
	s_mov_b64 s[6:7], -1
